# strategy 7 continued: NSA v_pk_mul_f32 (pass-2 normalisation, rescale paths) also split into single f32 multiplies
# baseline (speedup 1.0000x reference)
.LBB0_705:
	s_waitcnt vmcnt(4)
	v_lshlrev_b32_e32 v24, 16, v4
	v_and_b32_e32 v25, 0xffff0000, v4
	s_mov_b32 s4, 0x3e38aa3b
	v_mul_f32_e64 v24, v24, s4
	v_mul_f32_e64 v25, v25, s4
	v_add_u32_e32 v3, 1, v22
	v_cvt_pk_bf16_f32 v4, v24, v25
	v_lshlrev_b32_e32 v24, 16, v5
	v_and_b32_e32 v25, 0xffff0000, v5
	v_mul_f32_e64 v24, v24, s4
	v_mul_f32_e64 v25, v25, s4
	s_and_b32 s49, s2, 31
	v_cvt_pk_bf16_f32 v5, v24, v25
	v_lshlrev_b32_e32 v24, 16, v6
	v_and_b32_e32 v25, 0xffff0000, v6
	v_mul_f32_e64 v24, v24, s4
	v_mul_f32_e64 v25, v25, s4
	v_cvt_f32_ubyte0_e32 v3, v3
	v_cvt_pk_bf16_f32 v6, v24, v25
	v_lshlrev_b32_e32 v24, 16, v7
	v_and_b32_e32 v25, 0xffff0000, v7
	v_mul_f32_e64 v24, v24, s4
	v_mul_f32_e64 v25, v25, s4
	s_mov_b32 s2, 0x42fc0000
	v_cvt_pk_bf16_f32 v7, v24, v25
	s_waitcnt vmcnt(3)
	v_lshlrev_b32_e32 v24, 16, v8
	v_and_b32_e32 v25, 0xffff0000, v8
	v_mul_f32_e64 v24, v24, s4
	v_mul_f32_e64 v25, v25, s4
	v_cmp_lt_f32_e32 vcc, s2, v3
	v_cvt_pk_bf16_f32 v8, v24, v25
	v_lshlrev_b32_e32 v24, 16, v9
	v_and_b32_e32 v25, 0xffff0000, v9
	v_mul_f32_e64 v24, v24, s4
	v_mul_f32_e64 v25, v25, s4
	s_lshl_b32 s48, s49, 5
	v_cvt_pk_bf16_f32 v9, v24, v25
	v_lshlrev_b32_e32 v24, 16, v10
	v_and_b32_e32 v25, 0xffff0000, v10
	v_mul_f32_e64 v24, v24, s4
	v_mul_f32_e64 v25, v25, s4
	s_sub_i32 s13, s44, 31
	v_cvt_pk_bf16_f32 v10, v24, v25
	v_lshlrev_b32_e32 v24, 16, v11
	v_and_b32_e32 v25, 0xffff0000, v11
	v_mul_f32_e64 v24, v24, s4
	v_mul_f32_e64 v25, v25, s4
	s_movk_i32 s4, 0x48
	v_cvt_pk_bf16_f32 v11, v24, v25
	v_mad_u64_u32 v[24:25], s[4:5], v2, s4, v[20:21]
	s_lshl_b32 s4, s49, 1
	s_lshl_b32 s5, s46, 1
	v_cndmask_b32_e32 v20, 0, v248, vcc
	s_sub_i32 s4, s5, s4
	v_sub_f32_e32 v3, v20, v3
	s_addk_i32 s4, 0x7e
	v_exp_f32_e32 v3, v3
	s_lshr_b32 s4, s4, 6
	s_mov_b32 s5, s89
	s_lshl_b64 s[6:7], s[4:5], 13
	v_not_b32_e32 v20, 63
	s_add_u32 s6, s88, s6
	v_cndmask_b32_e32 v20, 0, v20, vcc
	s_addc_u32 s7, 0, s7
	v_and_b32_e32 v87, 7, v67
	v_ldexp_f32 v3, v3, v20
	v_or_b32_e32 v58, 0x10800, v0
	v_lshlrev_b32_e32 v98, 2, v21
	v_or_b32_e32 v57, 0x12c00, v0
	v_lshlrev_b32_e32 v59, 6, v21
	v_lshl_add_u64 v[20:21], s[6:7], 0, v[44:45]
	v_lshlrev_b32_e32 v0, 4, v87
	v_readlane_b32 s6, v254, 45
	v_lshl_add_u64 v[20:21], v[20:21], 0, v[0:1]
	v_readlane_b32 s7, v254, 46
	s_mul_i32 s5, s4, 0xfffffc0
	s_lshl_b32 s50, s46, 5
	v_lshl_add_u64 v[50:51], s[6:7], 0, v[20:21]
	v_sub_u32_e32 v20, s5, v98
	s_add_i32 s5, s43, s50
	v_add_u32_e32 v73, 0xf000003f, v20
	v_add_u32_e32 v20, s5, v120
	v_subrev_u32_e32 v90, s48, v20
	v_mul_f32_e32 v96, 0x3fb8aa3b, v3
	v_sub_u32_e32 v20, v90, v59
	s_lshl_b32 s4, s4, 10
	v_lshlrev_b32_e32 v55, 1, v24
	v_subrev_u32_e32 v38, 31, v103
	v_mul_f32_e32 v60, 0x41800000, v96
	v_subrev_u32_e32 v20, s4, v20
	s_add_i32 s4, s4, -16
	v_mov_b32_e32 v74, 0
	s_mov_b32 s2, 0
	v_add_u32_e32 v112, 0x10800, v55
	v_add_u32_e32 v113, 0x12c00, v55
	v_mul_u32_u24_e32 v56, 0x90, v54
	v_not_b32_e32 v99, v98
	v_add_u32_e32 v3, 0xffffffb1, v103
	v_subrev_u32_e32 v62, 63, v103
	v_add_u32_e32 v39, 0xfffffed1, v103
	v_add_u32_e32 v40, 0xfffffee1, v103
	v_add_u32_e32 v41, 0xfffffeb1, v103
	v_add_u32_e32 v42, 0xfffffec1, v103
	v_add_u32_e32 v63, 0xfffffdd1, v103
	v_add_u32_e32 v64, 0xfffffde1, v103
	v_add_u32_e32 v65, 0xfffffdb1, v103
	v_add_u32_e32 v66, 0xfffffdc1, v103
	v_add_u32_e32 v43, 0xfffffcd1, v103
	v_add_u32_e32 v46, 0xfffffce1, v103
	v_add_u32_e32 v47, 0xfffffcb1, v103
	v_add_u32_e32 v48, 0xfffffcc1, v103
	v_sub_u32_e32 v72, v38, v59
	v_mov_b32_e32 v97, v96
	v_mov_b32_e32 v49, v38
	v_mov_b32_e32 v61, v60
	v_mov_b32_e32 v68, v60
	v_mov_b32_e32 v69, v60
	v_mov_b32_e32 v70, v60
	v_mov_b32_e32 v71, v60
	v_add_u32_e32 v75, 0x7c1, v20
	v_mov_b32_e32 v89, 0xf149f2ca
	v_mov_b32_e32 v76, s4
	s_waitcnt vmcnt(0)
	ds_write_b128 v112, v[12:15]
	s_waitcnt lgkmcnt(0)
	s_barrier
	s_branch .LBB0_708

.LBB0_747:
	ds_read_b128 v[160:163], v118
	ds_read_b128 v[164:167], v118 offset:64
	ds_read_b128 v[168:171], v118 offset:2304
	ds_read_b128 v[172:175], v118 offset:2368
	ds_read_b128 v[176:179], v118 offset:4608
	ds_read_b128 v[180:183], v118 offset:4672
	ds_read_b128 v[184:187], v118 offset:6912
	ds_read_b128 v[188:191], v118 offset:6976
	v_cndmask_b32_e64 v78, 0, 1, s[4:5]
	s_mov_b64 s[6:7], -1
	v_cmp_ne_u32_e64 s[10:11], 1, v78
	s_andn2_b64 vcc, exec, s[4:5]
	s_waitcnt lgkmcnt(7)
	v_mfma_f32_16x16x32_bf16 v[52:55], v[160:163], v[4:7], v[52:55]
	s_waitcnt lgkmcnt(6)
	v_mfma_f32_16x16x32_bf16 v[52:55], v[164:167], v[8:11], v[52:55]
	ds_read_b128 v[196:199], v243
	ds_read_b128 v[200:203], v243 offset:64
	s_waitcnt lgkmcnt(7)
	v_mfma_f32_16x16x32_bf16 v[56:59], v[168:171], v[4:7], v[56:59]
	s_waitcnt lgkmcnt(6)
	v_mfma_f32_16x16x32_bf16 v[56:59], v[172:175], v[8:11], v[56:59]
	ds_read_b128 v[204:207], v243 offset:2304
	ds_read_b128 v[208:211], v243 offset:2368
	s_waitcnt lgkmcnt(7)
	v_mfma_f32_16x16x32_bf16 v[44:47], v[176:179], v[4:7], v[44:47]
	s_waitcnt lgkmcnt(6)
	v_mfma_f32_16x16x32_bf16 v[44:47], v[180:183], v[8:11], v[44:47]
	ds_read_b128 v[212:215], v243 offset:4608
	ds_read_b128 v[216:219], v243 offset:4672
	s_waitcnt lgkmcnt(7)
	v_mfma_f32_16x16x32_bf16 v[48:51], v[184:187], v[4:7], v[48:51]
	s_waitcnt lgkmcnt(6)
	v_mfma_f32_16x16x32_bf16 v[48:51], v[188:191], v[8:11], v[48:51]
	ds_read_b128 v[220:223], v243 offset:6912
	ds_read_b128 v[224:227], v243 offset:6976
	s_cbranch_vccnz .LBB0_749
	v_exp_f32_e32 v78, v52
	v_exp_f32_e32 v79, v56
	v_exp_f32_e32 v106, v53
	v_exp_f32_e32 v107, v57
	v_mul_f32_e32 v109, v74, v78
	v_mul_f32_e32 v110, v74, v79
	v_exp_f32_e32 v78, v54
	v_exp_f32_e32 v84, v58
	v_exp_f32_e32 v79, v55
	v_exp_f32_e32 v85, v59
	v_mul_f32_e32 v111, v74, v106
	v_mul_f32_e32 v121, v74, v107
	v_mul_f32_e64 v78, v74, v78
	v_mul_f32_e64 v79, v75, v79
	v_mul_f32_e64 v84, v74, v84
	v_mul_f32_e64 v85, v75, v85
	s_mov_b64 s[6:7], 0
.LBB0_749:
	s_andn2_b64 vcc, exec, s[6:7]
	v_add_u32_e32 v108, s14, v81
	s_cbranch_vccnz .LBB0_751
	v_add_u32_e32 v78, v81, v90
	v_add_u32_e32 v79, 0x3c1, v78
	v_cvt_f32_u32_e32 v84, v79
	v_add_u32_e32 v85, 0x2c1, v78
	v_cvt_f32_u32_e32 v85, v85
	v_cmp_lt_i32_e32 vcc, -1, v79
	v_fma_f32 v52, -v96, v84, v52
	v_sub_f32_e32 v52, v52, v89
	v_fma_f32 v56, -v96, v85, v56
	v_exp_f32_e32 v52, v52
	v_sub_f32_e32 v56, v56, v89
	v_exp_f32_e32 v56, v56
	v_add_u32_e32 v84, 0x3b1, v78
	v_mul_f32_e32 v52, v74, v52
	v_cndmask_b32_e32 v109, 0, v52, vcc
	v_mul_f32_e32 v52, v74, v56
	v_cvt_f32_u32_e32 v56, v84
	v_cmp_lt_i32_e32 vcc, s33, v79
	v_add_u32_e32 v106, v108, v62
	v_add_u32_e32 v85, v108, v3
	v_cndmask_b32_e32 v110, 0, v52, vcc
	v_add_u32_e32 v52, 0x2b1, v78
	v_fma_f32 v53, -v96, v56, v53
	v_cvt_f32_u32_e32 v52, v52
	v_sub_f32_e32 v53, v53, v89
	v_exp_f32_e32 v53, v53
	v_cmp_lt_i32_e32 vcc, -1, v84
	v_fma_f32 v52, -v96, v52, v57
	v_sub_f32_e32 v52, v52, v89
	v_mul_f32_e32 v53, v74, v53
	v_exp_f32_e32 v52, v52
	v_cndmask_b32_e32 v111, 0, v53, vcc
	v_add_u32_e32 v53, 0xffffff00, v106
	v_cvt_f32_u32_e32 v53, v53
	v_mul_f32_e32 v78, v74, v52
	v_cvt_f32_u32_e32 v52, v106
	v_cmp_lt_i32_e32 vcc, s33, v84
	v_fma_f32 v53, -v96, v53, v58
	v_sub_f32_e32 v53, v53, v89
	v_exp_f32_e32 v56, v53
	v_cvt_f32_u32_e32 v53, v85
	v_fma_f32 v52, -v96, v52, v54
	v_add_u32_e32 v54, 0xffffff00, v85
	v_cvt_f32_u32_e32 v54, v54
	v_fma_f32 v53, -v96, v53, v55
	v_sub_f32_e32 v52, v52, v89
	v_sub_f32_e32 v53, v53, v89
	v_exp_f32_e32 v52, v52
	v_fma_f32 v54, -v96, v54, v59
	v_exp_f32_e32 v53, v53
	v_sub_f32_e32 v54, v54, v89
	v_exp_f32_e32 v57, v54
	v_cndmask_b32_e32 v121, 0, v78, vcc
	v_mul_f32_e64 v52, v74, v52
	v_mul_f32_e64 v53, v75, v53
	v_cmp_lt_i32_e32 vcc, -1, v85
	v_mul_f32_e64 v54, v74, v56
	v_mul_f32_e64 v55, v75, v57
	s_nop 0
	v_cndmask_b32_e32 v79, 0, v53, vcc
	v_cmp_lt_i32_e32 vcc, -1, v106
	s_nop 1
	v_cndmask_b32_e32 v78, 0, v52, vcc
	v_cmp_lt_i32_e32 vcc, s33, v85
	s_nop 1
	v_cndmask_b32_e32 v85, 0, v55, vcc
	v_cmp_lt_i32_e32 vcc, s33, v106
	s_nop 1
	v_cndmask_b32_e32 v84, 0, v54, vcc

.LBB0_753:
	s_or_b64 exec, exec, s[4:5]
	s_and_b64 vcc, exec, s[10:11]
	s_mov_b64 s[4:5], -1
	s_cbranch_vccnz .LBB0_755
	v_exp_f32_e32 v52, v44
	v_exp_f32_e32 v54, v48
	v_exp_f32_e32 v53, v45
	v_exp_f32_e32 v55, v49
	v_exp_f32_e32 v56, v46
	v_exp_f32_e32 v58, v50
	v_exp_f32_e32 v57, v47
	v_exp_f32_e32 v59, v51
	v_mul_f32_e64 v52, v74, v52
	v_mul_f32_e64 v53, v75, v53
	v_mul_f32_e64 v54, v74, v54
	v_mul_f32_e64 v55, v75, v55
	v_mul_f32_e64 v56, v74, v56
	v_mul_f32_e64 v57, v75, v57
	v_mul_f32_e64 v58, v74, v58
	v_mul_f32_e64 v59, v75, v59
	s_cbranch_execz .LBB0_756
	s_branch .LBB0_757

.LBB0_756:
	v_add_u32_e32 v54, v108, v64
	v_add_u32_e32 v53, 0xffffff00, v54
	v_cvt_f32_u32_e32 v53, v53
	v_cvt_f32_u32_e32 v52, v54
	v_add_u32_e32 v55, v108, v63
	v_cmp_lt_i32_e32 vcc, -1, v55
	v_fma_f32 v48, -v96, v53, v48
	v_cvt_f32_u32_e32 v53, v55
	v_fma_f32 v44, -v96, v52, v44
	v_add_u32_e32 v52, 0xffffff00, v55
	v_cvt_f32_u32_e32 v52, v52
	v_fma_f32 v45, -v96, v53, v45
	v_sub_f32_e32 v44, v44, v89
	v_sub_f32_e32 v45, v45, v89
	v_exp_f32_e32 v44, v44
	v_fma_f32 v49, -v96, v52, v49
	v_exp_f32_e32 v45, v45
	v_sub_f32_e32 v48, v48, v89
	v_sub_f32_e32 v49, v49, v89
	v_exp_f32_e32 v48, v48
	v_exp_f32_e32 v49, v49
	v_mul_f32_e64 v44, v74, v44
	v_mul_f32_e64 v45, v75, v45
	v_add_u32_e32 v58, v108, v65
	v_cndmask_b32_e32 v53, 0, v45, vcc
	v_cmp_lt_i32_e32 vcc, -1, v54
	v_mul_f32_e64 v48, v74, v48
	v_mul_f32_e64 v49, v75, v49
	s_nop 0
	v_cndmask_b32_e32 v52, 0, v44, vcc
	v_cmp_lt_i32_e32 vcc, s33, v55
	s_nop 1
	v_cndmask_b32_e32 v55, 0, v49, vcc
	v_add_u32_e32 v49, v108, v66
	v_add_u32_e32 v45, 0xffffff00, v49
	v_cvt_f32_u32_e32 v45, v45
	v_cvt_f32_u32_e32 v44, v49
	v_cmp_lt_i32_e32 vcc, s33, v54
	v_fma_f32 v45, -v96, v45, v50
	v_sub_f32_e32 v45, v45, v89
	v_exp_f32_e32 v50, v45
	v_cvt_f32_u32_e32 v45, v58
	v_fma_f32 v44, -v96, v44, v46
	v_add_u32_e32 v46, 0xffffff00, v58
	v_cvt_f32_u32_e32 v46, v46
	v_fma_f32 v45, -v96, v45, v47
	v_sub_f32_e32 v44, v44, v89
	v_sub_f32_e32 v45, v45, v89
	v_exp_f32_e32 v44, v44
	v_fma_f32 v46, -v96, v46, v51
	v_exp_f32_e32 v45, v45
	v_sub_f32_e32 v46, v46, v89
	v_exp_f32_e32 v51, v46
	v_cndmask_b32_e32 v54, 0, v48, vcc
	v_mul_f32_e64 v44, v74, v44
	v_mul_f32_e64 v45, v75, v45
	v_cmp_lt_i32_e32 vcc, -1, v58
	v_mul_f32_e64 v46, v74, v50
	v_mul_f32_e64 v47, v75, v51
	s_nop 0
	v_cndmask_b32_e32 v57, 0, v45, vcc
	v_cmp_lt_i32_e32 vcc, -1, v49
	s_nop 1
	v_cndmask_b32_e32 v56, 0, v44, vcc
	v_cmp_lt_i32_e32 vcc, s33, v58
	s_nop 1
	v_cndmask_b32_e32 v59, 0, v47, vcc
	v_cmp_lt_i32_e32 vcc, s33, v49
	s_nop 1
	v_cndmask_b32_e32 v58, 0, v46, vcc

.LBB0_766:
	ds_read_b128 v[160:163], v119
	ds_read_b128 v[164:167], v119 offset:64
	ds_read_b128 v[168:171], v119 offset:2304
	ds_read_b128 v[172:175], v119 offset:2368
	ds_read_b128 v[176:179], v119 offset:4608
	ds_read_b128 v[180:183], v119 offset:4672
	ds_read_b128 v[184:187], v119 offset:6912
	ds_read_b128 v[188:191], v119 offset:6976
	v_cndmask_b32_e64 v78, 0, 1, s[4:5]
	s_mov_b64 s[6:7], -1
	v_cmp_ne_u32_e64 s[10:11], 1, v78
	s_andn2_b64 vcc, exec, s[4:5]
	s_waitcnt lgkmcnt(7)
	v_mfma_f32_16x16x32_bf16 v[52:55], v[160:163], v[4:7], v[52:55]
	s_waitcnt lgkmcnt(6)
	v_mfma_f32_16x16x32_bf16 v[52:55], v[164:167], v[8:11], v[52:55]
	ds_read_b128 v[196:199], v244
	ds_read_b128 v[200:203], v244 offset:64
	s_waitcnt lgkmcnt(7)
	v_mfma_f32_16x16x32_bf16 v[56:59], v[168:171], v[4:7], v[56:59]
	s_waitcnt lgkmcnt(6)
	v_mfma_f32_16x16x32_bf16 v[56:59], v[172:175], v[8:11], v[56:59]
	ds_read_b128 v[204:207], v244 offset:2304
	ds_read_b128 v[208:211], v244 offset:2368
	s_waitcnt lgkmcnt(7)
	v_mfma_f32_16x16x32_bf16 v[44:47], v[176:179], v[4:7], v[44:47]
	s_waitcnt lgkmcnt(6)
	v_mfma_f32_16x16x32_bf16 v[44:47], v[180:183], v[8:11], v[44:47]
	ds_read_b128 v[212:215], v244 offset:4608
	ds_read_b128 v[216:219], v244 offset:4672
	s_waitcnt lgkmcnt(7)
	v_mfma_f32_16x16x32_bf16 v[48:51], v[184:187], v[4:7], v[48:51]
	s_waitcnt lgkmcnt(6)
	v_mfma_f32_16x16x32_bf16 v[48:51], v[188:191], v[8:11], v[48:51]
	ds_read_b128 v[220:223], v244 offset:6912
	ds_read_b128 v[224:227], v244 offset:6976
	s_cbranch_vccnz .LBB0_768
	v_exp_f32_e32 v78, v52
	v_exp_f32_e32 v79, v56
	v_exp_f32_e32 v111, v53
	v_exp_f32_e32 v121, v57
	v_mul_f32_e32 v109, v74, v78
	v_mul_f32_e32 v110, v74, v79
	v_exp_f32_e32 v78, v54
	v_exp_f32_e32 v84, v58
	v_exp_f32_e32 v79, v55
	v_exp_f32_e32 v85, v59
	v_mul_f32_e32 v111, v74, v111
	v_mul_f32_e32 v121, v74, v121
	v_mul_f32_e64 v78, v74, v78
	v_mul_f32_e64 v79, v75, v79
	v_mul_f32_e64 v84, v74, v84
	v_mul_f32_e64 v85, v75, v85
	s_mov_b64 s[6:7], 0
.LBB0_768:
	s_andn2_b64 vcc, exec, s[6:7]
	v_add_u32_e32 v108, 0xfffffc00, v108
	s_cbranch_vccnz .LBB0_770
	v_add_u32_e32 v78, v81, v90
	v_subrev_u32_e32 v79, 63, v78
	v_cvt_f32_u32_e32 v84, v79
	v_add_u32_e32 v85, 0xfffffec1, v78
	v_cvt_f32_u32_e32 v85, v85
	v_cmp_lt_i32_e32 vcc, -1, v79
	v_fma_f32 v52, -v96, v84, v52
	v_sub_f32_e32 v52, v52, v89
	v_fma_f32 v56, -v96, v85, v56
	v_exp_f32_e32 v52, v52
	v_sub_f32_e32 v56, v56, v89
	v_exp_f32_e32 v56, v56
	v_add_u32_e32 v84, 0xffffffb1, v78
	v_mul_f32_e32 v52, v74, v52
	v_cndmask_b32_e32 v109, 0, v52, vcc
	v_mul_f32_e32 v52, v74, v56
	v_cvt_f32_u32_e32 v56, v84
	v_cmp_lt_i32_e32 vcc, s33, v79
	v_add_u32_e32 v122, v108, v62
	v_add_u32_e32 v85, v108, v3
	v_cndmask_b32_e32 v110, 0, v52, vcc
	v_add_u32_e32 v52, 0xfffffeb1, v78
	v_fma_f32 v53, -v96, v56, v53
	v_cvt_f32_u32_e32 v52, v52
	v_sub_f32_e32 v53, v53, v89
	v_exp_f32_e32 v53, v53
	v_cmp_lt_i32_e32 vcc, -1, v84
	v_fma_f32 v52, -v96, v52, v57
	v_sub_f32_e32 v52, v52, v89
	v_mul_f32_e32 v53, v74, v53
	v_exp_f32_e32 v52, v52
	v_cndmask_b32_e32 v111, 0, v53, vcc
	v_add_u32_e32 v53, 0xffffff00, v122
	v_cvt_f32_u32_e32 v53, v53
	v_mul_f32_e32 v78, v74, v52
	v_cvt_f32_u32_e32 v52, v122
	v_cmp_lt_i32_e32 vcc, s33, v84
	v_fma_f32 v53, -v96, v53, v58
	v_sub_f32_e32 v53, v53, v89
	v_exp_f32_e32 v56, v53
	v_cvt_f32_u32_e32 v53, v85
	v_fma_f32 v52, -v96, v52, v54
	v_add_u32_e32 v54, 0xffffff00, v85
	v_cvt_f32_u32_e32 v54, v54
	v_fma_f32 v53, -v96, v53, v55
	v_sub_f32_e32 v52, v52, v89
	v_sub_f32_e32 v53, v53, v89
	v_exp_f32_e32 v52, v52
	v_fma_f32 v54, -v96, v54, v59
	v_exp_f32_e32 v53, v53
	v_sub_f32_e32 v54, v54, v89
	v_exp_f32_e32 v57, v54
	v_cndmask_b32_e32 v121, 0, v78, vcc
	v_mul_f32_e64 v52, v74, v52
	v_mul_f32_e64 v53, v75, v53
	v_cmp_lt_i32_e32 vcc, -1, v85
	v_mul_f32_e64 v54, v74, v56
	v_mul_f32_e64 v55, v75, v57
	s_nop 0
	v_cndmask_b32_e32 v79, 0, v53, vcc
	v_cmp_lt_i32_e32 vcc, -1, v122
	s_nop 1
	v_cndmask_b32_e32 v78, 0, v52, vcc
	v_cmp_lt_i32_e32 vcc, s33, v85
	s_nop 1
	v_cndmask_b32_e32 v85, 0, v55, vcc
	v_cmp_lt_i32_e32 vcc, s33, v122
	s_nop 1
	v_cndmask_b32_e32 v84, 0, v54, vcc

.LBB0_972:
	v_mov_b32_e32 v60, s14
	ds_read_b32 v60, v60 offset:12
	ds_read_b128 v[160:163], v118
	ds_read_b128 v[164:167], v118 offset:64
	ds_read_b128 v[168:171], v118 offset:2304
	ds_read_b128 v[172:175], v118 offset:2368
	ds_read_b128 v[176:179], v118 offset:4608
	ds_read_b128 v[180:183], v118 offset:4672
	ds_read_b128 v[184:187], v118 offset:6912
	ds_read_b128 v[188:191], v118 offset:6976
	s_waitcnt lgkmcnt(8)
	v_ashrrev_i32_e32 v62, 5, v60
	v_lshlrev_b32_e32 v61, 2, v62
	v_add_u32_e32 v61, s13, v61
	ds_read_b32 v63, v61
	v_lshl_add_u32 v62, v62, 2, v105
	ds_read_b32 v62, v62 offset:8256
	v_lshlrev_b32_e64 v61, v60, 1
	s_waitcnt lgkmcnt(0)
	v_and_b32_e32 v63, v61, v63
	v_cmp_eq_u32_e32 vcc, 0, v63
	s_cbranch_vccnz .LBB0_982
	v_lshlrev_b32_e32 v108, 6, v60
	v_cmp_le_i32_e32 vcc, s51, v60
	s_and_b64 vcc, exec, vcc
	s_mov_b64 s[4:5], -1
	v_and_b32_e32 v60, v62, v61
	v_cmp_ne_u32_e64 s[8:9], 0, v60
	s_cbranch_vccz .LBB0_977
	ds_read_b128 v[60:63], v118
	ds_read_b128 v[64:67], v118 offset:64
	v_sub_u32_e32 v109, v103, v108
	v_mov_b32_e32 v131, v107
	s_waitcnt lgkmcnt(1)
	v_mfma_f32_16x16x32_bf16 v[60:63], v[60:63], v[4:7], 0
	ds_read_b128 v[72:75], v118 offset:6976
	s_waitcnt lgkmcnt(1)
	v_mfma_f32_16x16x32_bf16 v[76:79], v[64:67], v[8:11], v[60:63]
	ds_read_b128 v[64:67], v118 offset:2368
	s_nop 3
	ds_read_b128 v[60:63], v118 offset:2304
	s_waitcnt lgkmcnt(0)
	v_mfma_f32_16x16x32_bf16 v[60:63], v[60:63], v[4:7], 0
	v_mfma_f32_16x16x32_bf16 v[68:71], v[64:67], v[8:11], v[60:63]
	ds_read_b128 v[64:67], v118 offset:4672
	s_nop 5
	ds_read_b128 v[60:63], v118 offset:4608
	s_waitcnt lgkmcnt(0)
	v_mfma_f32_16x16x32_bf16 v[60:63], v[60:63], v[4:7], 0
	v_mfma_f32_16x16x32_bf16 v[64:67], v[64:67], v[8:11], v[60:63]
	s_nop 6
	ds_read_b128 v[60:63], v118 offset:6912
	s_waitcnt lgkmcnt(0)
	v_mfma_f32_16x16x32_bf16 v[60:63], v[60:63], v[4:7], 0
	v_mfma_f32_16x16x32_bf16 v[60:63], v[72:75], v[8:11], v[60:63]
	v_sub_u32_e32 v72, v109, v98
	v_cvt_f32_u32_e32 v73, v72
	v_cmp_gt_u32_e32 vcc, 2.0, v72
	s_and_b64 vcc, vcc, s[8:9]
	v_sub_u32_e32 v74, v109, v102
	v_fma_f32 v73, -v96, v73, v76
	v_cndmask_b32_e32 v76, v249, v73, vcc
	v_add_u32_e32 v73, v109, v99
	v_cmp_gt_u32_e32 vcc, 2.0, v73
	v_cvt_f32_u32_e32 v73, v73
	s_and_b64 vcc, vcc, s[8:9]
	v_fma_f32 v73, -v96, v73, v77
	v_cndmask_b32_e32 v77, v249, v73, vcc
	v_cmp_gt_u32_e32 vcc, 2.0, v74
	v_cvt_f32_u32_e32 v74, v74
	s_and_b64 vcc, vcc, s[8:9]
	v_max3_f32 v73, v76, s36, v77
	v_fma_f32 v74, -v96, v74, v78
	v_cndmask_b32_e32 v78, v249, v74, vcc
	v_sub_u32_e32 v74, v109, v101
	v_cmp_gt_u32_e32 vcc, 2.0, v74
	v_cvt_f32_u32_e32 v74, v74
	s_and_b64 vcc, vcc, s[8:9]
	v_mov_b32_e32 v109, v106
	v_fma_f32 v74, -v96, v74, v79
	v_cndmask_b32_e32 v79, v249, v74, vcc
	v_add_u32_e32 v74, -16, v72
	v_cmp_gt_u32_e32 vcc, 2.0, v74
	v_cvt_f32_u32_e32 v74, v74
	s_and_b64 vcc, vcc, s[8:9]
	v_max3_f32 v73, v73, v78, v79
	v_fma_f32 v68, -v96, v74, v68
	v_cndmask_b32_e32 v110, v249, v68, vcc
	v_subrev_u32_e32 v68, 17, v72
	v_cmp_gt_u32_e32 vcc, 2.0, v68
	v_cvt_f32_u32_e32 v68, v68
	s_and_b64 vcc, vcc, s[8:9]
	v_fma_f32 v68, -v96, v68, v69
	v_subrev_u32_e32 v69, 18, v72
	v_cndmask_b32_e32 v111, v249, v68, vcc
	v_cmp_gt_u32_e32 vcc, 2.0, v69
	v_cvt_f32_u32_e32 v69, v69
	s_and_b64 vcc, vcc, s[8:9]
	v_max3_f32 v68, v73, v110, v111
	v_fma_f32 v69, -v96, v69, v70
	v_cndmask_b32_e32 v121, v249, v69, vcc
	v_subrev_u32_e32 v69, 19, v72
	v_cmp_gt_u32_e32 vcc, 2.0, v69
	v_cvt_f32_u32_e32 v69, v69
	s_and_b64 vcc, vcc, s[8:9]
	v_fma_f32 v69, -v96, v69, v71
	v_cndmask_b32_e32 v122, v249, v69, vcc
	v_subrev_u32_e32 v69, 32, v72
	v_cmp_gt_u32_e32 vcc, 2.0, v69
	v_cvt_f32_u32_e32 v69, v69
	s_and_b64 vcc, vcc, s[8:9]
	v_max3_f32 v68, v68, v121, v122
	v_fma_f32 v64, -v96, v69, v64
	v_cndmask_b32_e32 v123, v249, v64, vcc
	v_subrev_u32_e32 v64, 33, v72
	v_cmp_gt_u32_e32 vcc, 2.0, v64
	v_cvt_f32_u32_e32 v64, v64
	s_and_b64 vcc, vcc, s[8:9]
	v_fma_f32 v64, -v96, v64, v65
	v_subrev_u32_e32 v65, 34, v72
	v_cndmask_b32_e32 v124, v249, v64, vcc
	v_cmp_gt_u32_e32 vcc, 2.0, v65
	v_cvt_f32_u32_e32 v65, v65
	s_and_b64 vcc, vcc, s[8:9]
	v_max3_f32 v64, v68, v123, v124
	v_mov_b64_e32 v[70:71], v[38:39]
	v_fma_f32 v65, -v96, v65, v66
	v_cndmask_b32_e32 v125, v249, v65, vcc
	v_subrev_u32_e32 v65, 35, v72
	v_cmp_gt_u32_e32 vcc, 2.0, v65
	v_cvt_f32_u32_e32 v65, v65
	s_and_b64 vcc, vcc, s[8:9]
	v_mov_b64_e32 v[68:69], v[36:37]
	v_fma_f32 v65, -v96, v65, v67
	v_cndmask_b32_e32 v126, v249, v65, vcc
	v_subrev_u32_e32 v65, 48, v72
	v_cmp_gt_u32_e32 vcc, 2.0, v65
	v_cvt_f32_u32_e32 v65, v65
	s_and_b64 vcc, vcc, s[8:9]
	v_max3_f32 v64, v64, v125, v126
	v_fma_f32 v60, -v96, v65, v60
	v_cndmask_b32_e32 v127, v249, v60, vcc
	v_subrev_u32_e32 v60, 49, v72
	v_cmp_gt_u32_e32 vcc, 2.0, v60
	v_cvt_f32_u32_e32 v60, v60
	s_and_b64 vcc, vcc, s[8:9]
	v_fma_f32 v60, -v96, v60, v61
	v_subrev_u32_e32 v61, 50, v72
	v_cndmask_b32_e32 v128, v249, v60, vcc
	v_cmp_gt_u32_e32 vcc, 2.0, v61
	v_cvt_f32_u32_e32 v61, v61
	s_and_b64 vcc, vcc, s[8:9]
	v_max3_f32 v60, v64, v127, v128
	v_mov_b64_e32 v[66:67], v[34:35]
	v_fma_f32 v61, -v96, v61, v62
	v_cndmask_b32_e32 v129, v249, v61, vcc
	v_subrev_u32_e32 v61, 51, v72
	v_cmp_gt_u32_e32 vcc, 2.0, v61
	v_cvt_f32_u32_e32 v61, v61
	s_and_b64 vcc, vcc, s[8:9]
	v_mov_b64_e32 v[74:75], v[42:43]
	v_mov_b64_e32 v[64:65], v[32:33]
	v_fma_f32 v61, -v96, v61, v63
	v_cndmask_b32_e32 v130, v249, v61, vcc
	v_max3_f32 v132, v60, v129, v130
	v_mov_b64_e32 v[62:63], v[30:31]
	v_cmp_gt_f32_e32 vcc, v132, v106
	v_mov_b64_e32 v[60:61], v[28:29]
	v_mov_b64_e32 v[72:73], v[40:41]
	s_cbranch_vccz .LBB0_976
	ds_bpermute_b32 v60, v115, v132
	v_max_f32_e32 v61, v132, v132
	s_waitcnt lgkmcnt(0)
	v_max_f32_e32 v60, v60, v60
	v_max_f32_e32 v60, v61, v60
	ds_bpermute_b32 v61, v114, v60
	s_waitcnt lgkmcnt(0)
	v_max3_f32 v109, v106, v60, v61
	v_sub_f32_e32 v60, v106, v109
	v_exp_f32_e32 v60, v60
	s_nop 0
	v_mul_f32_e32 v131, v107, v60
	v_mul_f32_e64 v74, v42, v60
	v_mul_f32_e64 v75, v43, v60
	v_mul_f32_e64 v72, v40, v60
	v_mul_f32_e64 v73, v41, v60
	v_mul_f32_e64 v70, v38, v60
	v_mul_f32_e64 v71, v39, v60
	v_mul_f32_e64 v68, v36, v60
	v_mul_f32_e64 v69, v37, v60
	v_mul_f32_e64 v66, v34, v60
	v_mul_f32_e64 v67, v35, v60
	v_mul_f32_e64 v64, v32, v60
	v_mul_f32_e64 v65, v33, v60
	v_mul_f32_e64 v62, v30, v60
	v_mul_f32_e64 v63, v31, v60
	v_mul_f32_e64 v61, v29, v60
	v_mul_f32_e64 v60, v28, v60

.LBB0_977:
	s_and_b64 vcc, exec, s[4:5]
	s_cbranch_vccz .LBB0_981
	s_nop 5
	v_or_b32_e32 v60, v98, v108
	v_sub_u32_e32 v60, v103, v60
	v_cvt_f32_i32_e32 v60, v60
	s_mov_b32 s4, 2.0
	s_mov_b32 s5, 0x40400000
	v_fma_f32 v60, -v96, v60, -v106
	v_cndmask_b32_e64 v68, v249, v60, s[8:9]
	v_fma_f32 v62, v96, s4, v68
	v_fma_f32 v63, v97, s5, v68
	s_mov_b32 s4, 0x41800000
	s_mov_b32 s5, 0x41880000
	v_fma_f32 v60, 0, v96, v68
	v_add_f32_e32 v61, v96, v68
	v_fma_f32 v66, v90, s90, v68
	v_fma_f32 v67, v91, s91, v68
	v_fma_f32 v64, v88, s4, v68
	v_fma_f32 v65, v89, s5, v68
	v_fma_f32 v78, v90, s92, v68
	v_fma_f32 v79, v91, s93, v68
	v_fma_f32 v76, v88, s34, v68
	v_fma_f32 v77, v89, s35, v68
	v_fma_f32 v110, v90, s22, v68
	v_fma_f32 v111, v91, s23, v68
	v_fma_f32 v108, v88, s72, v68
	v_fma_f32 v109, v89, s73, v68
	s_waitcnt lgkmcnt(7)
	v_mfma_f32_16x16x32_bf16 v[60:63], v[160:163], v[4:7], v[60:63]
	s_waitcnt lgkmcnt(6)
	v_mfma_f32_16x16x32_bf16 v[72:75], v[164:167], v[8:11], v[60:63]
	ds_read_b128 v[196:199], v243
	ds_read_b128 v[200:203], v243 offset:64
	s_waitcnt lgkmcnt(7)
	v_mfma_f32_16x16x32_bf16 v[60:63], v[168:171], v[4:7], v[64:67]
	s_waitcnt lgkmcnt(6)
	v_mfma_f32_16x16x32_bf16 v[68:71], v[172:175], v[8:11], v[60:63]
	ds_read_b128 v[204:207], v243 offset:2304
	ds_read_b128 v[208:211], v243 offset:2368
	s_waitcnt lgkmcnt(7)
	v_mfma_f32_16x16x32_bf16 v[60:63], v[176:179], v[4:7], v[76:79]
	s_waitcnt lgkmcnt(6)
	v_mfma_f32_16x16x32_bf16 v[60:63], v[180:183], v[8:11], v[60:63]
	ds_read_b128 v[212:215], v243 offset:4608
	ds_read_b128 v[216:219], v243 offset:4672
	s_waitcnt lgkmcnt(7)
	v_mfma_f32_16x16x32_bf16 v[64:67], v[184:187], v[4:7], v[108:111]
	s_waitcnt lgkmcnt(6)
	v_mfma_f32_16x16x32_bf16 v[64:67], v[188:191], v[8:11], v[64:67]
	ds_read_b128 v[220:223], v243 offset:6912
	ds_read_b128 v[224:227], v243 offset:6976
	v_max3_f32 v76, v72, s36, v73
	v_max3_f32 v76, v76, v74, v75
	v_max3_f32 v76, v76, v68, v69
	v_max3_f32 v76, v76, v70, v71
	v_max3_f32 v76, v76, v60, v61
	v_max3_f32 v76, v76, v62, v63
	s_nop 1
	v_max3_f32 v76, v76, v64, v65
	v_max3_f32 v76, v76, v66, v67
	v_cmp_lt_f32_e32 vcc, 0, v76
	s_cbranch_vccz .LBB0_980
	ds_bpermute_b32 v77, v115, v76
	v_max_f32_e32 v76, v76, v76
	s_waitcnt lgkmcnt(0)
	v_max_f32_e32 v77, v77, v77
	v_max_f32_e32 v76, v76, v77
	ds_bpermute_b32 v77, v114, v76
	s_waitcnt lgkmcnt(0)
	v_max3_f32 v77, 0, v76, v77
	v_sub_f32_e32 v76, 0, v77
	v_exp_f32_e32 v76, v76
	v_add_f32_e32 v106, v106, v77
	v_mul_f32_e32 v107, v107, v76
	v_mul_f32_e64 v42, v42, v76
	v_mul_f32_e64 v43, v43, v76
	v_mul_f32_e64 v40, v40, v76
	v_mul_f32_e64 v41, v41, v76
	v_mul_f32_e64 v38, v38, v76
	v_mul_f32_e64 v39, v39, v76
	v_mul_f32_e64 v36, v36, v76
	v_mul_f32_e64 v37, v37, v76
	v_mul_f32_e64 v34, v34, v76
	v_mul_f32_e64 v35, v35, v76
	v_mul_f32_e64 v32, v32, v76
	v_mul_f32_e64 v33, v33, v76
	v_mul_f32_e64 v30, v30, v76
	v_mul_f32_e64 v31, v31, v76
	v_mul_f32_e64 v28, v28, v76
	v_mul_f32_e64 v29, v29, v76
	v_sub_f32_e32 v72, v72, v77
	v_sub_f32_e32 v73, v73, v77
	v_sub_f32_e32 v74, v74, v77
	v_sub_f32_e32 v75, v75, v77
	v_sub_f32_e32 v68, v68, v77
	v_sub_f32_e32 v69, v69, v77
	v_sub_f32_e32 v70, v70, v77
	v_sub_f32_e32 v71, v71, v77
	v_sub_f32_e32 v60, v60, v77
	v_sub_f32_e32 v61, v61, v77
	v_sub_f32_e32 v62, v62, v77
	v_sub_f32_e32 v63, v63, v77
	v_sub_f32_e32 v64, v64, v77
	v_sub_f32_e32 v65, v65, v77
	v_sub_f32_e32 v66, v66, v77
	v_sub_f32_e32 v67, v67, v77

.LBB0_987:
	s_xor_b32 s2, s16, 0x3ffffffe
	s_lshl_b32 s2, s2, 2
	s_add_i32 s2, s12, s2
	v_mov_b32_e32 v60, s2
	ds_read_b32 v60, v60
	ds_read_b128 v[160:163], v119
	ds_read_b128 v[164:167], v119 offset:64
	ds_read_b128 v[168:171], v119 offset:2304
	ds_read_b128 v[172:175], v119 offset:2368
	ds_read_b128 v[176:179], v119 offset:4608
	ds_read_b128 v[180:183], v119 offset:4672
	ds_read_b128 v[184:187], v119 offset:6912
	ds_read_b128 v[188:191], v119 offset:6976
	s_waitcnt lgkmcnt(8)
	v_ashrrev_i32_e32 v62, 5, v60
	v_lshlrev_b32_e32 v61, 2, v62
	v_add_u32_e32 v61, s13, v61
	ds_read_b32 v63, v61
	v_lshl_add_u32 v62, v62, 2, v105
	ds_read_b32 v62, v62 offset:8256
	v_lshlrev_b32_e64 v61, v60, 1
	s_waitcnt lgkmcnt(0)
	v_and_b32_e32 v63, v61, v63
	v_cmp_eq_u32_e32 vcc, 0, v63
	s_cbranch_vccnz .LBB0_997
	v_lshlrev_b32_e32 v108, 6, v60
	v_cmp_le_i32_e32 vcc, s51, v60
	s_and_b64 vcc, exec, vcc
	s_mov_b64 s[4:5], -1
	v_and_b32_e32 v60, v62, v61
	v_cmp_ne_u32_e64 s[8:9], 0, v60
	s_cbranch_vccz .LBB0_992
	ds_read_b128 v[60:63], v119
	ds_read_b128 v[64:67], v119 offset:64
	v_sub_u32_e32 v109, v103, v108
	v_mov_b32_e32 v131, v107
	s_waitcnt lgkmcnt(1)
	v_mfma_f32_16x16x32_bf16 v[60:63], v[60:63], v[4:7], 0
	ds_read_b128 v[72:75], v119 offset:6976
	s_waitcnt lgkmcnt(1)
	v_mfma_f32_16x16x32_bf16 v[76:79], v[64:67], v[8:11], v[60:63]
	ds_read_b128 v[64:67], v119 offset:2368
	s_nop 3
	ds_read_b128 v[60:63], v119 offset:2304
	s_waitcnt lgkmcnt(0)
	v_mfma_f32_16x16x32_bf16 v[60:63], v[60:63], v[4:7], 0
	v_mfma_f32_16x16x32_bf16 v[68:71], v[64:67], v[8:11], v[60:63]
	ds_read_b128 v[64:67], v119 offset:4672
	s_nop 5
	ds_read_b128 v[60:63], v119 offset:4608
	s_waitcnt lgkmcnt(0)
	v_mfma_f32_16x16x32_bf16 v[60:63], v[60:63], v[4:7], 0
	v_mfma_f32_16x16x32_bf16 v[64:67], v[64:67], v[8:11], v[60:63]
	s_nop 6
	ds_read_b128 v[60:63], v119 offset:6912
	s_waitcnt lgkmcnt(0)
	v_mfma_f32_16x16x32_bf16 v[60:63], v[60:63], v[4:7], 0
	v_mfma_f32_16x16x32_bf16 v[60:63], v[72:75], v[8:11], v[60:63]
	v_sub_u32_e32 v72, v109, v98
	v_cvt_f32_u32_e32 v73, v72
	v_cmp_gt_u32_e32 vcc, 2.0, v72
	s_and_b64 vcc, vcc, s[8:9]
	v_sub_u32_e32 v74, v109, v102
	v_fma_f32 v73, -v96, v73, v76
	v_cndmask_b32_e32 v76, v249, v73, vcc
	v_add_u32_e32 v73, v109, v99
	v_cmp_gt_u32_e32 vcc, 2.0, v73
	v_cvt_f32_u32_e32 v73, v73
	s_and_b64 vcc, vcc, s[8:9]
	v_fma_f32 v73, -v96, v73, v77
	v_cndmask_b32_e32 v77, v249, v73, vcc
	v_cmp_gt_u32_e32 vcc, 2.0, v74
	v_cvt_f32_u32_e32 v74, v74
	s_and_b64 vcc, vcc, s[8:9]
	v_max3_f32 v73, v76, s36, v77
	v_fma_f32 v74, -v96, v74, v78
	v_cndmask_b32_e32 v78, v249, v74, vcc
	v_sub_u32_e32 v74, v109, v101
	v_cmp_gt_u32_e32 vcc, 2.0, v74
	v_cvt_f32_u32_e32 v74, v74
	s_and_b64 vcc, vcc, s[8:9]
	v_mov_b32_e32 v109, v106
	v_fma_f32 v74, -v96, v74, v79
	v_cndmask_b32_e32 v79, v249, v74, vcc
	v_add_u32_e32 v74, -16, v72
	v_cmp_gt_u32_e32 vcc, 2.0, v74
	v_cvt_f32_u32_e32 v74, v74
	s_and_b64 vcc, vcc, s[8:9]
	v_max3_f32 v73, v73, v78, v79
	v_fma_f32 v68, -v96, v74, v68
	v_cndmask_b32_e32 v110, v249, v68, vcc
	v_subrev_u32_e32 v68, 17, v72
	v_cmp_gt_u32_e32 vcc, 2.0, v68
	v_cvt_f32_u32_e32 v68, v68
	s_and_b64 vcc, vcc, s[8:9]
	v_fma_f32 v68, -v96, v68, v69
	v_subrev_u32_e32 v69, 18, v72
	v_cndmask_b32_e32 v111, v249, v68, vcc
	v_cmp_gt_u32_e32 vcc, 2.0, v69
	v_cvt_f32_u32_e32 v69, v69
	s_and_b64 vcc, vcc, s[8:9]
	v_max3_f32 v68, v73, v110, v111
	v_fma_f32 v69, -v96, v69, v70
	v_cndmask_b32_e32 v121, v249, v69, vcc
	v_subrev_u32_e32 v69, 19, v72
	v_cmp_gt_u32_e32 vcc, 2.0, v69
	v_cvt_f32_u32_e32 v69, v69
	s_and_b64 vcc, vcc, s[8:9]
	v_fma_f32 v69, -v96, v69, v71
	v_cndmask_b32_e32 v122, v249, v69, vcc
	v_subrev_u32_e32 v69, 32, v72
	v_cmp_gt_u32_e32 vcc, 2.0, v69
	v_cvt_f32_u32_e32 v69, v69
	s_and_b64 vcc, vcc, s[8:9]
	v_max3_f32 v68, v68, v121, v122
	v_fma_f32 v64, -v96, v69, v64
	v_cndmask_b32_e32 v123, v249, v64, vcc
	v_subrev_u32_e32 v64, 33, v72
	v_cmp_gt_u32_e32 vcc, 2.0, v64
	v_cvt_f32_u32_e32 v64, v64
	s_and_b64 vcc, vcc, s[8:9]
	v_fma_f32 v64, -v96, v64, v65
	v_subrev_u32_e32 v65, 34, v72
	v_cndmask_b32_e32 v124, v249, v64, vcc
	v_cmp_gt_u32_e32 vcc, 2.0, v65
	v_cvt_f32_u32_e32 v65, v65
	s_and_b64 vcc, vcc, s[8:9]
	v_max3_f32 v64, v68, v123, v124
	v_mov_b64_e32 v[70:71], v[38:39]
	v_fma_f32 v65, -v96, v65, v66
	v_cndmask_b32_e32 v125, v249, v65, vcc
	v_subrev_u32_e32 v65, 35, v72
	v_cmp_gt_u32_e32 vcc, 2.0, v65
	v_cvt_f32_u32_e32 v65, v65
	s_and_b64 vcc, vcc, s[8:9]
	v_mov_b64_e32 v[68:69], v[36:37]
	v_fma_f32 v65, -v96, v65, v67
	v_cndmask_b32_e32 v126, v249, v65, vcc
	v_subrev_u32_e32 v65, 48, v72
	v_cmp_gt_u32_e32 vcc, 2.0, v65
	v_cvt_f32_u32_e32 v65, v65
	s_and_b64 vcc, vcc, s[8:9]
	v_max3_f32 v64, v64, v125, v126
	v_fma_f32 v60, -v96, v65, v60
	v_cndmask_b32_e32 v127, v249, v60, vcc
	v_subrev_u32_e32 v60, 49, v72
	v_cmp_gt_u32_e32 vcc, 2.0, v60
	v_cvt_f32_u32_e32 v60, v60
	s_and_b64 vcc, vcc, s[8:9]
	v_fma_f32 v60, -v96, v60, v61
	v_subrev_u32_e32 v61, 50, v72
	v_cndmask_b32_e32 v128, v249, v60, vcc
	v_cmp_gt_u32_e32 vcc, 2.0, v61
	v_cvt_f32_u32_e32 v61, v61
	s_and_b64 vcc, vcc, s[8:9]
	v_max3_f32 v60, v64, v127, v128
	v_mov_b64_e32 v[66:67], v[34:35]
	v_fma_f32 v61, -v96, v61, v62
	v_cndmask_b32_e32 v129, v249, v61, vcc
	v_subrev_u32_e32 v61, 51, v72
	v_cmp_gt_u32_e32 vcc, 2.0, v61
	v_cvt_f32_u32_e32 v61, v61
	s_and_b64 vcc, vcc, s[8:9]
	v_mov_b64_e32 v[74:75], v[42:43]
	v_mov_b64_e32 v[64:65], v[32:33]
	v_fma_f32 v61, -v96, v61, v63
	v_cndmask_b32_e32 v130, v249, v61, vcc
	v_max3_f32 v132, v60, v129, v130
	v_mov_b64_e32 v[62:63], v[30:31]
	v_cmp_gt_f32_e32 vcc, v132, v106
	v_mov_b64_e32 v[60:61], v[28:29]
	v_mov_b64_e32 v[72:73], v[40:41]
	s_cbranch_vccz .LBB0_991
	ds_bpermute_b32 v60, v115, v132
	v_max_f32_e32 v61, v132, v132
	s_waitcnt lgkmcnt(0)
	v_max_f32_e32 v60, v60, v60
	v_max_f32_e32 v60, v61, v60
	ds_bpermute_b32 v61, v114, v60
	s_waitcnt lgkmcnt(0)
	v_max3_f32 v109, v106, v60, v61
	v_sub_f32_e32 v60, v106, v109
	v_exp_f32_e32 v60, v60
	s_nop 0
	v_mul_f32_e32 v131, v107, v60
	v_mul_f32_e64 v74, v42, v60
	v_mul_f32_e64 v75, v43, v60
	v_mul_f32_e64 v72, v40, v60
	v_mul_f32_e64 v73, v41, v60
	v_mul_f32_e64 v70, v38, v60
	v_mul_f32_e64 v71, v39, v60
	v_mul_f32_e64 v68, v36, v60
	v_mul_f32_e64 v69, v37, v60
	v_mul_f32_e64 v66, v34, v60
	v_mul_f32_e64 v67, v35, v60
	v_mul_f32_e64 v64, v32, v60
	v_mul_f32_e64 v65, v33, v60
	v_mul_f32_e64 v62, v30, v60
	v_mul_f32_e64 v63, v31, v60
	v_mul_f32_e64 v61, v29, v60
	v_mul_f32_e64 v60, v28, v60

.LBB0_992:
	s_and_b64 vcc, exec, s[4:5]
	s_cbranch_vccz .LBB0_996
	s_nop 5
	v_or_b32_e32 v60, v98, v108
	v_sub_u32_e32 v60, v103, v60
	v_cvt_f32_i32_e32 v60, v60
	s_mov_b32 s4, 2.0
	s_mov_b32 s5, 0x40400000
	v_fma_f32 v60, -v96, v60, -v106
	v_cndmask_b32_e64 v68, v249, v60, s[8:9]
	v_fma_f32 v62, v96, s4, v68
	v_fma_f32 v63, v97, s5, v68
	s_mov_b32 s4, 0x41800000
	s_mov_b32 s5, 0x41880000
	v_fma_f32 v60, 0, v96, v68
	v_add_f32_e32 v61, v96, v68
	v_fma_f32 v66, v90, s90, v68
	v_fma_f32 v67, v91, s91, v68
	v_fma_f32 v64, v88, s4, v68
	v_fma_f32 v65, v89, s5, v68
	v_fma_f32 v78, v90, s92, v68
	v_fma_f32 v79, v91, s93, v68
	v_fma_f32 v76, v88, s34, v68
	v_fma_f32 v77, v89, s35, v68
	v_fma_f32 v110, v90, s22, v68
	v_fma_f32 v111, v91, s23, v68
	v_fma_f32 v108, v88, s72, v68
	v_fma_f32 v109, v89, s73, v68
	s_waitcnt lgkmcnt(7)
	v_mfma_f32_16x16x32_bf16 v[60:63], v[160:163], v[4:7], v[60:63]
	s_waitcnt lgkmcnt(6)
	v_mfma_f32_16x16x32_bf16 v[72:75], v[164:167], v[8:11], v[60:63]
	ds_read_b128 v[196:199], v244
	ds_read_b128 v[200:203], v244 offset:64
	s_waitcnt lgkmcnt(7)
	v_mfma_f32_16x16x32_bf16 v[60:63], v[168:171], v[4:7], v[64:67]
	s_waitcnt lgkmcnt(6)
	v_mfma_f32_16x16x32_bf16 v[68:71], v[172:175], v[8:11], v[60:63]
	ds_read_b128 v[204:207], v244 offset:2304
	ds_read_b128 v[208:211], v244 offset:2368
	s_waitcnt lgkmcnt(7)
	v_mfma_f32_16x16x32_bf16 v[60:63], v[176:179], v[4:7], v[76:79]
	s_waitcnt lgkmcnt(6)
	v_mfma_f32_16x16x32_bf16 v[60:63], v[180:183], v[8:11], v[60:63]
	ds_read_b128 v[212:215], v244 offset:4608
	ds_read_b128 v[216:219], v244 offset:4672
	s_waitcnt lgkmcnt(7)
	v_mfma_f32_16x16x32_bf16 v[64:67], v[184:187], v[4:7], v[108:111]
	s_waitcnt lgkmcnt(6)
	v_mfma_f32_16x16x32_bf16 v[64:67], v[188:191], v[8:11], v[64:67]
	ds_read_b128 v[220:223], v244 offset:6912
	ds_read_b128 v[224:227], v244 offset:6976
	v_max3_f32 v76, v72, s36, v73
	v_max3_f32 v76, v76, v74, v75
	v_max3_f32 v76, v76, v68, v69
	v_max3_f32 v76, v76, v70, v71
	v_max3_f32 v76, v76, v60, v61
	v_max3_f32 v76, v76, v62, v63
	s_nop 1
	v_max3_f32 v76, v76, v64, v65
	v_max3_f32 v76, v76, v66, v67
	v_cmp_lt_f32_e32 vcc, 0, v76
	s_cbranch_vccz .LBB0_995
	ds_bpermute_b32 v77, v115, v76
	v_max_f32_e32 v76, v76, v76
	s_waitcnt lgkmcnt(0)
	v_max_f32_e32 v77, v77, v77
	v_max_f32_e32 v76, v76, v77
	ds_bpermute_b32 v77, v114, v76
	s_waitcnt lgkmcnt(0)
	v_max3_f32 v77, 0, v76, v77
	v_sub_f32_e32 v76, 0, v77
	v_exp_f32_e32 v76, v76
	v_add_f32_e32 v106, v106, v77
	v_mul_f32_e32 v107, v107, v76
	v_mul_f32_e64 v42, v42, v76
	v_mul_f32_e64 v43, v43, v76
	v_mul_f32_e64 v40, v40, v76
	v_mul_f32_e64 v41, v41, v76
	v_mul_f32_e64 v38, v38, v76
	v_mul_f32_e64 v39, v39, v76
	v_mul_f32_e64 v36, v36, v76
	v_mul_f32_e64 v37, v37, v76
	v_mul_f32_e64 v34, v34, v76
	v_mul_f32_e64 v35, v35, v76
	v_mul_f32_e64 v32, v32, v76
	v_mul_f32_e64 v33, v33, v76
	v_mul_f32_e64 v30, v30, v76
	v_mul_f32_e64 v31, v31, v76
	v_mul_f32_e64 v28, v28, v76
	v_mul_f32_e64 v29, v29, v76
	v_sub_f32_e32 v72, v72, v77
	v_sub_f32_e32 v73, v73, v77
	v_sub_f32_e32 v74, v74, v77
	v_sub_f32_e32 v75, v75, v77
	v_sub_f32_e32 v68, v68, v77
	v_sub_f32_e32 v69, v69, v77
	v_sub_f32_e32 v70, v70, v77
	v_sub_f32_e32 v71, v71, v77
	v_sub_f32_e32 v60, v60, v77
	v_sub_f32_e32 v61, v61, v77
	v_sub_f32_e32 v62, v62, v77
	v_sub_f32_e32 v63, v63, v77
	v_sub_f32_e32 v64, v64, v77
	v_sub_f32_e32 v65, v65, v77
	v_sub_f32_e32 v66, v66, v77
	v_sub_f32_e32 v67, v67, v77

.LBB0_1010:
	s_add_i32 s1, s14, s0
	s_addk_i32 s1, 0xc0
	s_cmp_ge_i32 s44, s1
	s_cselect_b64 s[4:5], -1, 0
	s_add_i32 s1, s43, s15
	s_cmpk_lt_i32 s1, 0x200
	s_cselect_b64 s[20:21], -1, 0
	s_and_b64 s[4:5], s[4:5], s[20:21]
	s_andn2_b64 vcc, exec, s[4:5]
	s_mov_b64 s[4:5], -1
	s_cbranch_vccz .LBB0_1024
	ds_read_b128 v[76:79], v118
	ds_read_b128 v[80:83], v118 offset:64
	ds_read_b128 v[84:87], v118 offset:2304
	ds_read_b128 v[88:91], v118 offset:2368
	v_add_u32_e32 v0, s43, v125
	s_waitcnt lgkmcnt(3)
	v_mfma_f32_16x16x32_bf16 v[76:79], v[76:79], v[4:7], 0
	ds_read_b128 v[128:131], v118 offset:4608
	ds_read_b128 v[132:135], v118 offset:4672
	v_sub_u32_e32 v146, v0, v98
	v_add_u32_e32 v136, v0, v99
	s_waitcnt lgkmcnt(4)
	v_mfma_f32_16x16x32_bf16 v[76:79], v[80:83], v[8:11], v[76:79]
	v_cvt_f32_u32_e32 v3, v136
	v_cvt_f32_u32_e32 v2, v146
	v_cmp_gt_u32_e32 vcc, s83, v136
	s_waitcnt lgkmcnt(3)
	v_mfma_f32_16x16x32_bf16 v[84:87], v[84:87], v[4:7], 0
	v_sub_u32_e32 v136, v0, v101
	v_sub_u32_e32 v0, v0, v102
	s_nop 0
	v_fma_f32 v2, -v96, v2, v76
	v_fma_f32 v3, -v97, v3, v77
	s_waitcnt lgkmcnt(2)
	v_mfma_f32_16x16x32_bf16 v[80:83], v[88:91], v[8:11], v[84:87]
	s_nop 2
	ds_read_b128 v[84:87], v118 offset:6912
	ds_read_b128 v[88:91], v118 offset:6976
	v_cvt_f32_u32_e32 v77, v136
	v_cvt_f32_u32_e32 v76, v0
	s_waitcnt lgkmcnt(1)
	v_mfma_f32_16x16x32_bf16 v[84:87], v[84:87], v[4:7], 0
	v_cndmask_b32_e32 v3, v249, v3, vcc
	v_cmp_gt_u32_e32 vcc, s83, v146
	v_fma_f32 v76, -v96, v76, v78
	v_fma_f32 v77, -v97, v77, v79
	v_mfma_f32_16x16x32_bf16 v[128:131], v[128:131], v[4:7], 0
	s_waitcnt lgkmcnt(0)
	v_mfma_f32_16x16x32_bf16 v[84:87], v[88:91], v[8:11], v[84:87]
	v_subrev_u32_e32 v88, 17, v146
	v_add_u32_e32 v89, -16, v146
	v_cvt_f32_u32_e32 v79, v88
	v_cvt_f32_u32_e32 v78, v89
	v_mfma_f32_16x16x32_bf16 v[142:145], v[132:135], v[8:11], v[128:131]
	s_nop 2
	v_cndmask_b32_e32 v130, v249, v2, vcc
	v_cmp_gt_u32_e32 vcc, s83, v136
	v_max3_f32 v2, v130, s36, v3
	s_nop 0
	v_cndmask_b32_e32 v128, v249, v77, vcc
	v_cmp_gt_u32_e32 vcc, s83, v0
	s_nop 1
	v_cndmask_b32_e32 v135, v249, v76, vcc
	v_max3_f32 v0, v2, v135, v128
	v_fma_f32 v76, -v96, v78, v80
	v_fma_f32 v77, -v97, v79, v81
	v_subrev_u32_e32 v2, 19, v146
	v_subrev_u32_e32 v80, 18, v146
	v_cvt_f32_u32_e32 v79, v2
	v_cvt_f32_u32_e32 v78, v80
	v_cmp_gt_u32_e32 vcc, s83, v88
	v_subrev_u32_e32 v81, 32, v146
	s_nop 0
	v_cndmask_b32_e32 v129, v249, v77, vcc
	v_cmp_gt_u32_e32 vcc, s83, v89
	v_mov_b64_e32 v[90:91], v[74:75]
	v_mov_b64_e32 v[88:89], v[72:73]
	v_cndmask_b32_e32 v137, v249, v76, vcc
	v_cmp_gt_u32_e32 vcc, s83, v2
	v_subrev_u32_e32 v2, 33, v146
	v_fma_f32 v76, -v96, v78, v82
	v_fma_f32 v77, -v97, v79, v83
	v_cvt_f32_u32_e32 v79, v2
	v_cvt_f32_u32_e32 v78, v81
	v_cndmask_b32_e32 v134, v249, v77, vcc
	v_cmp_gt_u32_e32 vcc, s83, v80
	v_subrev_u32_e32 v80, 34, v146
	v_max3_f32 v0, v0, v137, v129
	v_cndmask_b32_e32 v140, v249, v76, vcc
	v_cmp_gt_u32_e32 vcc, s83, v2
	v_subrev_u32_e32 v2, 35, v146
	v_fma_f32 v76, -v96, v78, v142
	v_fma_f32 v77, -v97, v79, v143
	v_cvt_f32_u32_e32 v79, v2
	v_cvt_f32_u32_e32 v78, v80
	v_cndmask_b32_e32 v131, v249, v77, vcc
	v_cmp_gt_u32_e32 vcc, s83, v81
	v_subrev_u32_e32 v81, 48, v146
	v_max3_f32 v0, v0, v140, v134
	v_cndmask_b32_e32 v139, v249, v76, vcc
	v_cmp_gt_u32_e32 vcc, s83, v2
	v_subrev_u32_e32 v2, 49, v146
	v_fma_f32 v76, -v96, v78, v144
	v_fma_f32 v77, -v97, v79, v145
	v_cvt_f32_u32_e32 v79, v2
	v_cvt_f32_u32_e32 v78, v81
	v_cndmask_b32_e32 v136, v249, v77, vcc
	v_cmp_gt_u32_e32 vcc, s83, v80
	v_subrev_u32_e32 v80, 50, v146
	v_max3_f32 v0, v0, v139, v131
	v_cndmask_b32_e32 v141, v249, v76, vcc
	v_cmp_gt_u32_e32 vcc, s83, v2
	v_subrev_u32_e32 v2, 51, v146
	v_fma_f32 v76, -v96, v78, v84
	v_fma_f32 v77, -v97, v79, v85
	v_cvt_f32_u32_e32 v79, v2
	v_cvt_f32_u32_e32 v78, v80
	v_cndmask_b32_e32 v138, v249, v77, vcc
	v_cmp_gt_u32_e32 vcc, s83, v81
	v_max3_f32 v0, v0, v141, v136
	s_nop 0
	v_cndmask_b32_e32 v142, v249, v76, vcc
	v_fma_f32 v76, -v96, v78, v86
	v_fma_f32 v77, -v97, v79, v87
	v_cmp_gt_u32_e32 vcc, s83, v2
	v_max3_f32 v0, v0, v142, v138
	v_mov_b64_e32 v[86:87], v[70:71]
	v_cndmask_b32_e32 v133, v249, v77, vcc
	v_cmp_gt_u32_e32 vcc, s83, v80
	v_mov_b64_e32 v[82:83], v[66:67]
	v_mov_b64_e32 v[84:85], v[68:69]
	v_cndmask_b32_e32 v132, v249, v76, vcc
	v_max3_f32 v143, v0, v132, v133
	v_mov_b64_e32 v[78:79], v[62:63]
	v_cmp_gt_f32_e32 vcc, v143, v126
	v_mov_b64_e32 v[80:81], v[64:65]
	v_mov_b64_e32 v[76:77], v[60:61]
	v_mov_b32_e32 v2, v127
	v_mov_b32_e32 v0, v126
	s_cbranch_vccz .LBB0_1013
	ds_bpermute_b32 v0, v115, v143
	v_max_f32_e32 v2, v143, v143
	s_waitcnt lgkmcnt(0)
	v_max_f32_e32 v0, v0, v0
	v_max_f32_e32 v0, v2, v0
	ds_bpermute_b32 v2, v114, v0
	s_waitcnt lgkmcnt(0)
	v_max3_f32 v0, v126, v0, v2
	v_sub_f32_e32 v2, v126, v0
	v_exp_f32_e32 v88, v2
	s_nop 0
	v_mul_f32_e32 v2, v127, v88
	v_mul_f32_e64 v78, v62, v88
	v_mul_f32_e64 v79, v63, v88
	v_mul_f32_e64 v76, v60, v88
	v_mul_f32_e64 v77, v61, v88
	v_mul_f32_e64 v82, v66, v88
	v_mul_f32_e64 v83, v67, v88
	v_mul_f32_e64 v80, v64, v88
	v_mul_f32_e64 v81, v65, v88
	v_mul_f32_e64 v86, v70, v88
	v_mul_f32_e64 v87, v71, v88
	v_mul_f32_e64 v84, v68, v88
	v_mul_f32_e64 v85, v69, v88
	v_mul_f32_e64 v90, v74, v88
	v_mul_f32_e64 v91, v75, v88
	v_mul_f32_e64 v89, v73, v88
	v_mul_f32_e64 v88, v72, v88

.LBB0_1019:
	s_xor_b32 s1, s17, 0x3fffffe
	s_add_i32 s1, s1, s10
	s_lshl_b32 s1, s1, 6
	s_add_i32 s1, s1, s88
	s_or_b32 s2, s1, 63
	s_cmp_ge_i32 s44, s2
	s_cselect_b64 s[4:5], -1, 0
	s_sub_i32 s2, s13, s1
	s_cmpk_lt_i32 s2, 0x200
	s_cselect_b64 s[20:21], -1, 0
	s_and_b64 s[4:5], s[4:5], s[20:21]
	s_andn2_b64 vcc, exec, s[4:5]
	s_mov_b64 s[4:5], -1
	s_cbranch_vccz .LBB0_1029
	ds_read_b128 v[60:63], v119
	ds_read_b128 v[64:67], v119 offset:64
	ds_read_b128 v[68:71], v119 offset:2304
	ds_read_b128 v[72:75], v119 offset:2368
	v_subrev_u32_e32 v3, s1, v103
	s_waitcnt lgkmcnt(3)
	v_mfma_f32_16x16x32_bf16 v[60:63], v[60:63], v[4:7], 0
	v_sub_u32_e32 v146, v3, v98
	v_add_u32_e32 v138, v3, v99
	ds_read_b128 v[126:129], v119 offset:4608
	ds_read_b128 v[130:133], v119 offset:4672
	s_waitcnt lgkmcnt(4)
	v_mfma_f32_16x16x32_bf16 v[60:63], v[64:67], v[8:11], v[60:63]
	v_cvt_f32_u32_e32 v135, v138
	v_cvt_f32_u32_e32 v134, v146
	v_cmp_gt_u32_e32 vcc, s83, v138
	s_waitcnt lgkmcnt(3)
	v_mfma_f32_16x16x32_bf16 v[68:71], v[68:71], v[4:7], 0
	s_waitcnt lgkmcnt(2)
	v_mfma_f32_16x16x32_bf16 v[64:67], v[72:75], v[8:11], v[68:71]
	s_nop 5
	ds_read_b128 v[68:71], v119 offset:6912
	ds_read_b128 v[72:75], v119 offset:6976
	v_fma_f32 v60, -v96, v134, v60
	v_fma_f32 v61, -v97, v135, v61
	s_waitcnt lgkmcnt(3)
	v_mfma_f32_16x16x32_bf16 v[134:137], v[126:129], v[4:7], 0
	v_sub_u32_e32 v126, v3, v101
	v_sub_u32_e32 v3, v3, v102
	v_cvt_f32_u32_e32 v129, v126
	s_waitcnt lgkmcnt(1)
	v_mfma_f32_16x16x32_bf16 v[68:71], v[68:71], v[4:7], 0
	v_cvt_f32_u32_e32 v128, v3
	v_cndmask_b32_e32 v127, v249, v61, vcc
	v_cmp_gt_u32_e32 vcc, s83, v146
	s_waitcnt lgkmcnt(0)
	v_mfma_f32_16x16x32_bf16 v[68:71], v[72:75], v[8:11], v[68:71]
	v_subrev_u32_e32 v72, 17, v146
	v_add_u32_e32 v73, -16, v146
	v_mfma_f32_16x16x32_bf16 v[142:145], v[130:133], v[8:11], v[134:137]
	v_cndmask_b32_e32 v130, v249, v60, vcc
	v_fma_f32 v60, -v96, v128, v62
	v_fma_f32 v61, -v97, v129, v63
	v_cvt_f32_u32_e32 v63, v72
	v_cvt_f32_u32_e32 v62, v73
	v_cmp_gt_u32_e32 vcc, s83, v126
	v_max3_f32 v131, v130, s36, v127
	v_mov_b32_e32 v126, v0
	v_cndmask_b32_e32 v128, v249, v61, vcc
	v_cmp_gt_u32_e32 vcc, s83, v3
	s_nop 1
	v_cndmask_b32_e32 v135, v249, v60, vcc
	v_fma_f32 v60, -v96, v62, v64
	v_fma_f32 v61, -v97, v63, v65
	v_subrev_u32_e32 v64, 19, v146
	v_subrev_u32_e32 v65, 18, v146
	v_cvt_f32_u32_e32 v63, v64
	v_cvt_f32_u32_e32 v62, v65
	v_cmp_gt_u32_e32 vcc, s83, v72
	v_max3_f32 v3, v131, v135, v128
	s_nop 0
	v_cndmask_b32_e32 v129, v249, v61, vcc
	v_cmp_gt_u32_e32 vcc, s83, v73
	v_mov_b64_e32 v[72:73], v[88:89]
	v_mov_b64_e32 v[74:75], v[90:91]
	v_cndmask_b32_e32 v137, v249, v60, vcc
	v_fma_f32 v60, -v96, v62, v66
	v_fma_f32 v61, -v97, v63, v67
	v_cmp_gt_u32_e32 vcc, s83, v64
	v_subrev_u32_e32 v64, 33, v146
	v_subrev_u32_e32 v66, 32, v146
	v_cvt_f32_u32_e32 v63, v64
	v_cvt_f32_u32_e32 v62, v66
	v_cndmask_b32_e32 v134, v249, v61, vcc
	v_cmp_gt_u32_e32 vcc, s83, v65
	v_subrev_u32_e32 v65, 34, v146
	v_max3_f32 v3, v3, v137, v129
	v_cndmask_b32_e32 v140, v249, v60, vcc
	v_cmp_gt_u32_e32 vcc, s83, v64
	v_subrev_u32_e32 v64, 35, v146
	v_fma_f32 v60, -v96, v62, v142
	v_fma_f32 v61, -v97, v63, v143
	v_cvt_f32_u32_e32 v63, v64
	v_cvt_f32_u32_e32 v62, v65
	v_cndmask_b32_e32 v131, v249, v61, vcc
	v_cmp_gt_u32_e32 vcc, s83, v66
	v_subrev_u32_e32 v66, 48, v146
	v_max3_f32 v3, v3, v140, v134
	v_cndmask_b32_e32 v139, v249, v60, vcc
	v_cmp_gt_u32_e32 vcc, s83, v64
	v_subrev_u32_e32 v64, 49, v146
	v_fma_f32 v60, -v96, v62, v144
	v_fma_f32 v61, -v97, v63, v145
	v_cvt_f32_u32_e32 v63, v64
	v_cvt_f32_u32_e32 v62, v66
	v_cndmask_b32_e32 v136, v249, v61, vcc
	v_cmp_gt_u32_e32 vcc, s83, v65
	v_subrev_u32_e32 v65, 50, v146
	v_max3_f32 v3, v3, v139, v131
	v_cndmask_b32_e32 v141, v249, v60, vcc
	v_cmp_gt_u32_e32 vcc, s83, v64
	v_subrev_u32_e32 v64, 51, v146
	v_fma_f32 v60, -v96, v62, v68
	v_fma_f32 v61, -v97, v63, v69
	v_cvt_f32_u32_e32 v63, v64
	v_cvt_f32_u32_e32 v62, v65
	v_cndmask_b32_e32 v138, v249, v61, vcc
	v_cmp_gt_u32_e32 vcc, s83, v66
	v_max3_f32 v3, v3, v141, v136
	s_nop 0
	v_cndmask_b32_e32 v142, v249, v60, vcc
	v_fma_f32 v60, -v96, v62, v70
	v_fma_f32 v61, -v97, v63, v71
	v_cmp_gt_u32_e32 vcc, s83, v64
	v_max3_f32 v3, v3, v142, v138
	v_mov_b64_e32 v[68:69], v[84:85]
	v_cndmask_b32_e32 v133, v249, v61, vcc
	v_cmp_gt_u32_e32 vcc, s83, v65
	v_mov_b64_e32 v[64:65], v[80:81]
	v_mov_b64_e32 v[70:71], v[86:87]
	v_cndmask_b32_e32 v132, v249, v60, vcc
	v_max3_f32 v143, v3, v132, v133
	v_mov_b64_e32 v[60:61], v[76:77]
	v_cmp_gt_f32_e32 vcc, v143, v0
	v_mov_b64_e32 v[66:67], v[82:83]
	v_mov_b64_e32 v[62:63], v[78:79]
	v_mov_b32_e32 v3, v2
	s_cbranch_vccz .LBB0_1022
	ds_bpermute_b32 v3, v115, v143
	v_max_f32_e32 v60, v143, v143
	s_waitcnt lgkmcnt(0)
	v_max_f32_e32 v3, v3, v3
	v_max_f32_e32 v3, v60, v3
	ds_bpermute_b32 v60, v114, v3
	s_waitcnt lgkmcnt(0)
	v_max3_f32 v126, v0, v3, v60
	v_sub_f32_e32 v3, v0, v126
	v_exp_f32_e32 v72, v3
	s_nop 0
	v_mul_f32_e32 v3, v2, v72
	v_mul_f32_e64 v62, v78, v72
	v_mul_f32_e64 v63, v79, v72
	v_mul_f32_e64 v60, v76, v72
	v_mul_f32_e64 v61, v77, v72
	v_mul_f32_e64 v66, v82, v72
	v_mul_f32_e64 v67, v83, v72
	v_mul_f32_e64 v64, v80, v72
	v_mul_f32_e64 v65, v81, v72
	v_mul_f32_e64 v70, v86, v72
	v_mul_f32_e64 v71, v87, v72
	v_mul_f32_e64 v68, v84, v72
	v_mul_f32_e64 v69, v85, v72
	v_mul_f32_e64 v74, v90, v72
	v_mul_f32_e64 v75, v91, v72
	v_mul_f32_e64 v73, v89, v72
	v_mul_f32_e64 v72, v88, v72

.LBB0_1024:
	s_and_b64 vcc, exec, s[4:5]
	s_cbranch_vccz .LBB0_1014
	ds_read_b128 v[160:163], v118
	ds_read_b128 v[164:167], v118 offset:64
	ds_read_b128 v[168:171], v118 offset:2304
	ds_read_b128 v[172:175], v118 offset:2368
	ds_read_b128 v[176:179], v118 offset:4608
	ds_read_b128 v[180:183], v118 offset:4672
	ds_read_b128 v[184:187], v118 offset:6912
	ds_read_b128 v[188:191], v118 offset:6976
	v_add_u32_e32 v0, s43, v120
	v_cvt_f32_i32_e32 v2, v0
	s_mov_b32 s4, 2.0
	s_mov_b32 s5, 0x40400000
	v_mul_f32_e64 v0, -v96, v2
	v_mov_b32_e32 v76, v0
	v_fma_f32 v77, -v96, v2, v96
	v_fmac_f32_e32 v76, 0, v96
	v_fma_f32 v78, v96, s4, v0
	v_fma_f32 v79, v97, s5, v0
	s_mov_b32 s4, 0x41800000
	s_mov_b32 s5, 0x41880000
	s_waitcnt lgkmcnt(7)
	v_mfma_f32_16x16x32_bf16 v[76:79], v[160:163], v[4:7], v[76:79]
	v_fma_f32 v82, v108, s90, v0
	v_fma_f32 v83, v109, s91, v0
	v_fma_f32 v80, v106, s4, v0
	v_fma_f32 v81, v107, s5, v0
	v_fma_f32 v130, v108, s92, v0
	v_fma_f32 v131, v109, s93, v0
	s_waitcnt lgkmcnt(6)
	v_mfma_f32_16x16x32_bf16 v[88:91], v[164:167], v[8:11], v[76:79]
	ds_read_b128 v[196:199], v243
	ds_read_b128 v[200:203], v243 offset:64
	s_nop 2
	v_fma_f32 v128, v106, s34, v0
	v_fma_f32 v129, v107, s35, v0
	v_fma_f32 v134, v108, s22, v0
	v_fma_f32 v135, v109, s23, v0
	s_waitcnt lgkmcnt(7)
	v_mfma_f32_16x16x32_bf16 v[76:79], v[168:171], v[4:7], v[80:83]
	s_nop 2
	v_fma_f32 v132, v106, s72, v0
	v_fma_f32 v133, v107, s73, v0
	v_max3_f32 v0, v88, s36, v89
	s_waitcnt lgkmcnt(6)
	v_mfma_f32_16x16x32_bf16 v[84:87], v[172:175], v[8:11], v[76:79]
	ds_read_b128 v[204:207], v243 offset:2304
	ds_read_b128 v[208:211], v243 offset:2368
	s_nop 2
	v_max3_f32 v0, v0, v90, v91
	s_waitcnt lgkmcnt(7)
	v_mfma_f32_16x16x32_bf16 v[76:79], v[176:179], v[4:7], v[128:131]
	s_nop 2
	v_max3_f32 v0, v0, v84, v85
	v_max3_f32 v0, v0, v86, v87
	s_waitcnt lgkmcnt(6)
	v_mfma_f32_16x16x32_bf16 v[76:79], v[180:183], v[8:11], v[76:79]
	ds_read_b128 v[212:215], v243 offset:4608
	ds_read_b128 v[216:219], v243 offset:4672
	s_waitcnt lgkmcnt(7)
	v_mfma_f32_16x16x32_bf16 v[80:83], v[184:187], v[4:7], v[132:135]
	s_nop 4
	v_max3_f32 v0, v0, v76, v77
	v_max3_f32 v0, v0, v78, v79
	s_waitcnt lgkmcnt(6)
	v_mfma_f32_16x16x32_bf16 v[80:83], v[188:191], v[8:11], v[80:83]
	ds_read_b128 v[220:223], v243 offset:6912
	ds_read_b128 v[224:227], v243 offset:6976
	s_nop 7
	v_max3_f32 v0, v0, v80, v81
	v_max3_f32 v0, v0, v82, v83
	v_cmp_gt_f32_e32 vcc, v0, v126
	s_cbranch_vccz .LBB0_1027
	ds_bpermute_b32 v2, v115, v0
	v_max_f32_e32 v0, v0, v0
	s_waitcnt lgkmcnt(0)
	v_max_f32_e32 v2, v2, v2
	v_max_f32_e32 v0, v0, v2
	ds_bpermute_b32 v2, v114, v0
	s_waitcnt lgkmcnt(0)
	v_max3_f32 v2, v126, v0, v2
	v_sub_f32_e32 v0, v126, v2
	v_exp_f32_e32 v0, v0
	v_mov_b32_e32 v126, v2
	v_mul_f32_e32 v127, v127, v0
	v_mul_f32_e64 v62, v62, v0
	v_mul_f32_e64 v63, v63, v0
	v_mul_f32_e64 v60, v60, v0
	v_mul_f32_e64 v61, v61, v0
	v_mul_f32_e64 v66, v66, v0
	v_mul_f32_e64 v67, v67, v0
	v_mul_f32_e64 v64, v64, v0
	v_mul_f32_e64 v65, v65, v0
	v_mul_f32_e64 v70, v70, v0
	v_mul_f32_e64 v71, v71, v0
	v_mul_f32_e64 v68, v68, v0
	v_mul_f32_e64 v69, v69, v0
	v_mul_f32_e64 v74, v74, v0
	v_mul_f32_e64 v75, v75, v0
	v_mul_f32_e64 v72, v72, v0
	v_mul_f32_e64 v73, v73, v0

.LBB0_1029:
	s_and_b64 vcc, exec, s[4:5]
	s_cbranch_vccz .LBB0_1023
	ds_read_b128 v[160:163], v119
	ds_read_b128 v[164:167], v119 offset:64
	ds_read_b128 v[168:171], v119 offset:2304
	ds_read_b128 v[172:175], v119 offset:2368
	ds_read_b128 v[176:179], v119 offset:4608
	ds_read_b128 v[180:183], v119 offset:4672
	ds_read_b128 v[184:187], v119 offset:6912
	ds_read_b128 v[188:191], v119 offset:6976
	v_or_b32_e32 v3, s1, v98
	v_sub_u32_e32 v3, v103, v3
	v_cvt_f32_i32_e32 v3, v3
	s_mov_b32 s4, 2.0
	s_mov_b32 s5, 0x40400000
	v_mul_f32_e64 v68, -v96, v3
	v_fma_f32 v62, v96, s4, v68
	v_fma_f32 v63, v97, s5, v68
	s_mov_b32 s4, 0x41800000
	s_mov_b32 s5, 0x41880000
	v_mov_b32_e32 v60, v68
	v_fma_f32 v66, v108, s90, v68
	v_fma_f32 v67, v109, s91, v68
	v_fma_f32 v64, v106, s4, v68
	v_fma_f32 v65, v107, s5, v68
	v_fma_f32 v128, v108, s92, v68
	v_fma_f32 v129, v109, s93, v68
	v_fma_f32 v126, v106, s34, v68
	v_fma_f32 v127, v107, s35, v68
	v_fma_f32 v132, v108, s22, v68
	v_fma_f32 v133, v109, s23, v68
	v_fma_f32 v130, v106, s72, v68
	v_fma_f32 v131, v107, s73, v68
	v_fma_f32 v61, -v96, v3, v96
	v_fmac_f32_e32 v60, 0, v96
	s_nop 0
	s_waitcnt lgkmcnt(7)
	v_mfma_f32_16x16x32_bf16 v[60:63], v[160:163], v[4:7], v[60:63]
	s_waitcnt lgkmcnt(6)
	v_mfma_f32_16x16x32_bf16 v[72:75], v[164:167], v[8:11], v[60:63]
	ds_read_b128 v[196:199], v244
	ds_read_b128 v[200:203], v244 offset:64
	s_nop 4
	s_nop 1
	v_max3_f32 v3, v72, s36, v73
	s_waitcnt lgkmcnt(7)
	v_mfma_f32_16x16x32_bf16 v[60:63], v[168:171], v[4:7], v[64:67]
	s_nop 2
	v_max3_f32 v3, v3, v74, v75
	s_waitcnt lgkmcnt(6)
	v_mfma_f32_16x16x32_bf16 v[68:71], v[172:175], v[8:11], v[60:63]
	ds_read_b128 v[204:207], v244 offset:2304
	ds_read_b128 v[208:211], v244 offset:2368
	s_nop 2
	s_nop 2
	v_max3_f32 v3, v3, v68, v69
	s_waitcnt lgkmcnt(7)
	v_mfma_f32_16x16x32_bf16 v[60:63], v[176:179], v[4:7], v[126:129]
	s_nop 2
	v_max3_f32 v3, v3, v70, v71
	s_waitcnt lgkmcnt(6)
	v_mfma_f32_16x16x32_bf16 v[60:63], v[180:183], v[8:11], v[60:63]
	ds_read_b128 v[212:215], v244 offset:4608
	ds_read_b128 v[216:219], v244 offset:4672
	s_waitcnt lgkmcnt(7)
	v_mfma_f32_16x16x32_bf16 v[64:67], v[184:187], v[4:7], v[130:133]
	s_nop 4
	v_max3_f32 v3, v3, v60, v61
	v_max3_f32 v3, v3, v62, v63
	s_waitcnt lgkmcnt(6)
	v_mfma_f32_16x16x32_bf16 v[64:67], v[188:191], v[8:11], v[64:67]
	ds_read_b128 v[220:223], v244 offset:6912
	ds_read_b128 v[224:227], v244 offset:6976
	s_nop 7
	v_max3_f32 v3, v3, v64, v65
	v_max3_f32 v3, v3, v66, v67
	v_cmp_gt_f32_e32 vcc, v3, v0
	s_cbranch_vccz .LBB0_1032
	ds_bpermute_b32 v126, v115, v3
	v_max_f32_e32 v3, v3, v3
	s_waitcnt lgkmcnt(0)
	v_max_f32_e32 v126, v126, v126
	v_max_f32_e32 v3, v3, v126
	ds_bpermute_b32 v126, v114, v3
	s_waitcnt lgkmcnt(0)
	v_max3_f32 v3, v0, v3, v126
	v_sub_f32_e32 v0, v0, v3
	v_exp_f32_e32 v0, v0
	s_nop 0
	v_mul_f32_e32 v2, v2, v0
	v_mul_f32_e64 v78, v78, v0
	v_mul_f32_e64 v79, v79, v0
	v_mul_f32_e64 v76, v76, v0
	v_mul_f32_e64 v77, v77, v0
	v_mul_f32_e64 v82, v82, v0
	v_mul_f32_e64 v83, v83, v0
	v_mul_f32_e64 v80, v80, v0
	v_mul_f32_e64 v81, v81, v0
	v_mul_f32_e64 v86, v86, v0
	v_mul_f32_e64 v87, v87, v0
	v_mul_f32_e64 v84, v84, v0
	v_mul_f32_e64 v85, v85, v0
	v_mul_f32_e64 v90, v90, v0
	v_mul_f32_e64 v91, v91, v0
	v_mul_f32_e64 v88, v88, v0
	v_mul_f32_e64 v89, v89, v0
	v_mov_b32_e32 v0, v3
